# grid barrier behind P4: the first workgroup of every XCD to arrive starts an L2 write-back while it waits
# baseline (speedup 1.0000x reference)
.LBB0_713:
	s_or_b64 exec, exec, s[6:7]
	buffer_inv sc1
	v_cvt_f32_u32_e32 v5, v3
	s_waitcnt vmcnt(1)
	v_readfirstlane_b32 s4, v4
	v_sub_u32_e32 v4, 0, v3
	v_rcp_iflag_f32_e32 v5, v5
	v_add_u32_e32 v6, s4, v2
	v_mul_f32_e32 v5, 0x4f7ffffe, v5
	v_cvt_u32_f32_e32 v5, v5
	v_mul_lo_u32 v2, v4, v5
	v_mul_hi_u32 v2, v5, v2
	v_add_u32_e32 v2, v5, v2
	v_mul_hi_u32 v2, v6, v2
	v_mul_lo_u32 v4, v2, v3
	v_sub_u32_e32 v4, v6, v4
	v_add_u32_e32 v5, 1, v2
	v_cmp_ge_u32_e32 vcc, v4, v3
	s_nop 1
	v_cndmask_b32_e32 v2, v2, v5, vcc
	v_sub_u32_e32 v5, v4, v3
	v_cndmask_b32_e32 v4, v4, v5, vcc
	v_add_u32_e32 v5, 1, v2
	v_cmp_ge_u32_e32 vcc, v4, v3
	v_add_u32_e32 v4, 1, v6
	s_nop 0
	v_cndmask_b32_e32 v2, v2, v5, vcc
	v_mul_lo_u32 v5, v3, v2
	v_add_u32_e32 v3, v5, v3
	v_cmp_ne_u32_e32 vcc, v4, v3
	s_and_saveexec_b64 s[4:5], vcc
	s_xor_b64 s[4:5], exec, s[4:5]
	s_cbranch_execz .LBB0_727
	s_waitcnt lgkmcnt(0)
	v_sub_u32_e32 v7, v4, v5
	v_readfirstlane_b32 s6, v7
	s_cmp_lg_u32 s6, 1
	s_cbranch_scc1 .Lfa_skip
	buffer_wbl2 sc1
.Lfa_skip:
	v_mov_b32_e32 v1, 0x2000
	global_load_dword v1, v1, s[2:3] offset:1024 sc1
	s_add_u32 s10, s2, 0x2400
	s_addc_u32 s11, s3, 0
	s_waitcnt vmcnt(0)
	v_cmp_eq_u32_e32 vcc, v1, v2
	s_and_saveexec_b64 s[6:7], vcc
	s_cbranch_execz .LBB0_726
	s_add_u32 s8, s96, 0x1200
	s_addc_u32 s9, s97, 0
	s_mov_b32 s22, 1
	s_mov_b64 s[12:13], 0
	v_mov_b32_e32 v1, 0
	s_branch .LBB0_717
